# diff-attention tile loops: row max via v_max3 chain without canonicalising max(x,x), s_setprio toggles around the MFMAs removed (nop padding kept for the MFMA result hazard); on top of norm_gif fill b
# speedup vs baseline: 1.0190x; 1.0177x over previous
.LBB0_291:
	v_add_u32_e32 v0, s2, v199
	ds_read_b128 v[130:133], v0
	s_add_i32 s0, s47, -2
	ds_read_b128 v[188:191], v0 offset:1024
	s_waitcnt lgkmcnt(1)
	v_mfma_f32_32x32x16_bf16 v[130:145], v[130:133], v[146:149], 0
	ds_read_b128 v[248:251], v0 offset:2048
	s_waitcnt lgkmcnt(1)
	v_mfma_f32_32x32x16_bf16 v[130:145], v[188:191], v[150:153], v[130:145]
	ds_read_b128 v[188:191], v0 offset:3072
	s_cmp_lt_u32 s47, s44
	s_cbranch_scc0 .Lmy_a_nok1
	s_mov_b32 m0, s52
	s_nop 0
	global_load_lds_dwordx4 v[210:211], off
.Lmy_a_nok1:
	s_waitcnt lgkmcnt(1)
	v_mfma_f32_32x32x16_bf16 v[130:145], v[248:251], v[154:157], v[130:145]
	ds_read_b128 v[248:251], v0 offset:4096
	s_waitcnt lgkmcnt(1)
	v_mfma_f32_32x32x16_bf16 v[130:145], v[188:191], v[158:161], v[130:145]
	ds_read_b128 v[188:191], v0 offset:5120
	s_waitcnt lgkmcnt(1)
	v_mfma_f32_32x32x16_bf16 v[130:145], v[248:251], v[162:165], v[130:145]
	ds_read_b128 v[248:251], v0 offset:6144
	s_cmp_lt_u32 s47, s44
	s_cbranch_scc0 .Lmy_a_nok2
	s_mov_b32 m0, s53
	s_nop 0
	global_load_lds_dwordx4 v[208:209], off
.Lmy_a_nok2:
	s_waitcnt lgkmcnt(1)
	v_mfma_f32_32x32x16_bf16 v[130:145], v[188:191], v[166:169], v[130:145]
	ds_read_b128 v[188:191], v0 offset:7168
	s_waitcnt lgkmcnt(1)
	v_mfma_f32_32x32x16_bf16 v[130:145], v[248:251], v[170:173], v[130:145]
	s_waitcnt lgkmcnt(0)
	v_mfma_f32_32x32x16_bf16 v[130:145], v[188:191], v[174:177], v[130:145]
	s_cmp_lt_u32 s0, s43
	s_cbranch_scc1 .LBB0_293
	v_add_u32_e32 v0, s46, v223
	v_add_u32_e32 v187, 32, v0
	v_cmp_lt_u32_e32 vcc, v187, v201
	s_nop 7
	v_cndmask_b32_e32 v131, v246, v131, vcc
	v_cmp_le_u32_e32 vcc, v187, v201
	v_add_u32_e32 v187, 34, v0
	s_nop 0
	v_cndmask_b32_e32 v130, v246, v130, vcc
	v_cmp_le_u32_e32 vcc, v187, v201
	v_add_u32_e32 v187, 35, v0
	s_nop 0
	v_cndmask_b32_e32 v132, v246, v132, vcc
	v_cmp_le_u32_e32 vcc, v187, v201
	v_add_u32_e32 v187, 40, v0
	s_nop 0
	v_cndmask_b32_e32 v133, v246, v133, vcc
	v_cmp_le_u32_e32 vcc, v187, v201
	v_add_u32_e32 v187, 41, v0
	s_nop 0
	v_cndmask_b32_e32 v134, v246, v134, vcc
	v_cmp_le_u32_e32 vcc, v187, v201
	v_add_u32_e32 v187, 42, v0
	s_nop 0
	v_cndmask_b32_e32 v135, v246, v135, vcc
	v_cmp_le_u32_e32 vcc, v187, v201
	v_add_u32_e32 v187, 43, v0
	s_nop 0
	v_cndmask_b32_e32 v136, v246, v136, vcc
	v_cmp_le_u32_e32 vcc, v187, v201
	v_add_u32_e32 v187, 48, v0
	s_nop 0
	v_cndmask_b32_e32 v137, v246, v137, vcc
	v_cmp_le_u32_e32 vcc, v187, v201
	v_add_u32_e32 v187, 49, v0
	s_nop 0
	v_cndmask_b32_e32 v138, v246, v138, vcc
	v_cmp_le_u32_e32 vcc, v187, v201
	v_add_u32_e32 v187, 50, v0
	s_nop 0
	v_cndmask_b32_e32 v139, v246, v139, vcc
	v_cmp_le_u32_e32 vcc, v187, v201
	v_add_u32_e32 v187, 51, v0
	s_nop 0
	v_cndmask_b32_e32 v140, v246, v140, vcc
	v_cmp_le_u32_e32 vcc, v187, v201
	v_add_u32_e32 v187, 56, v0
	s_nop 0
	v_cndmask_b32_e32 v141, v246, v141, vcc
	v_cmp_le_u32_e32 vcc, v187, v201
	v_add_u32_e32 v187, 57, v0
	s_nop 0
	v_cndmask_b32_e32 v142, v246, v142, vcc
	v_cmp_le_u32_e32 vcc, v187, v201
	v_add_u32_e32 v187, 58, v0
	v_add_u32_e32 v0, 59, v0
	v_cndmask_b32_e32 v143, v246, v143, vcc
	v_cmp_le_u32_e32 vcc, v187, v201
	s_nop 1
	v_cndmask_b32_e32 v144, v246, v144, vcc
	v_cmp_le_u32_e32 vcc, v0, v201
	s_nop 1
	v_cndmask_b32_e32 v145, v246, v145, vcc
.LBB0_293:
	s_nop 9
	v_max3_f32 v0, v130, v131, v132
	v_max3_f32 v187, v133, v134, v135
	v_max3_f32 v188, v136, v137, v138
	v_max3_f32 v189, v139, v140, v141
	v_max3_f32 v0, v0, v142, v143
	v_max3_f32 v187, v187, v144, v145
	v_max3_f32 v0, v0, v187, v188
	v_max_f32_e32 v0, v0, v189
	v_mov_b32_e32 v187, v0
	s_nop 1
	v_permlane32_swap_b32_e32 v0, v187
	s_lshl_b32 s0, s49, 14
	v_max_f32_e32 v0, v0, v187
	v_add_f32_e32 v187, 0x41000000, v186
	s_add_i32 s3, s0, 0
	v_cmp_gt_f32_e32 vcc, v0, v187
	s_cmp_eq_u64 vcc, 0
	v_max_f32_e32 v0, v186, v0
	s_cselect_b64 s[0:1], -1, 0
	v_cndmask_b32_e64 v0, v0, v186, s[0:1]
	v_add_u32_e32 v252, s3, v224
	v_sub_f32_e32 v247, v186, v0
	v_add_u32_e32 v253, s3, v228
	ds_read_b64_tr_b16 v[186:187], v252 offset:49152
	ds_read_b64_tr_b16 v[188:189], v252 offset:53248
	ds_read_b64_tr_b16 v[190:191], v253 offset:49152
	ds_read_b64_tr_b16 v[192:193], v253 offset:53248
	v_exp_f32_e32 v247, v247
	v_add_u32_e32 v254, s3, v229
	ds_read_b64_tr_b16 v[248:249], v254 offset:49152
	ds_read_b64_tr_b16 v[250:251], v254 offset:53248
	s_waitcnt lgkmcnt(4)
	v_mfma_f32_32x32x16_bf16 v[114:129], v[182:185], v[186:189], v[114:129]
	v_add_u32_e32 v195, s3, v230
	ds_read_b64_tr_b16 v[186:187], v195 offset:49152
	ds_read_b64_tr_b16 v[188:189], v195 offset:53248
	v_sub_f32_e32 v130, v130, v0
	v_exp_f32_e32 v1, v130
	s_waitcnt lgkmcnt(4)
	v_mfma_f32_32x32x16_bf16 v[98:113], v[182:185], v[190:193], v[98:113]
	ds_read_b64_tr_b16 v[190:191], v252 offset:49408
	ds_read_b64_tr_b16 v[192:193], v252 offset:53504
	v_sub_f32_e32 v131, v131, v0
	v_exp_f32_e32 v131, v131
	v_add_f32_e32 v130, 0, v1
	s_waitcnt lgkmcnt(4)
	v_mfma_f32_32x32x16_bf16 v[82:97], v[182:185], v[248:251], v[82:97]
	ds_read_b64_tr_b16 v[248:249], v253 offset:49408
	ds_read_b64_tr_b16 v[250:251], v253 offset:53504
	v_sub_f32_e32 v132, v132, v0
	v_exp_f32_e32 v132, v132
	v_add_f32_e32 v130, v131, v130
	s_waitcnt lgkmcnt(4)
	v_mfma_f32_32x32x16_bf16 v[66:81], v[182:185], v[186:189], v[66:81]
	ds_read_b64_tr_b16 v[186:187], v254 offset:49408
	ds_read_b64_tr_b16 v[188:189], v254 offset:53504
	v_sub_f32_e32 v133, v133, v0
	v_exp_f32_e32 v133, v133
	v_add_f32_e32 v130, v132, v130
	s_cmp_le_u32 s47, s44
	s_cbranch_scc0 .Lmy_a_nov1
	s_mov_b32 m0, s54
	s_nop 0
	global_load_lds_dwordx4 v[206:207], off
.Lmy_a_nov1:
	s_waitcnt lgkmcnt(4)
	v_mfma_f32_32x32x16_bf16 v[50:65], v[182:185], v[190:193], v[50:65]
	ds_read_b64_tr_b16 v[190:191], v195 offset:49408
	ds_read_b64_tr_b16 v[192:193], v195 offset:53504
	v_sub_f32_e32 v134, v134, v0
	v_exp_f32_e32 v134, v134
	v_add_f32_e32 v130, v133, v130
	s_waitcnt lgkmcnt(4)
	v_mfma_f32_32x32x16_bf16 v[34:49], v[182:185], v[248:251], v[34:49]
	ds_read_b64_tr_b16 v[248:249], v252 offset:57344
	ds_read_b64_tr_b16 v[250:251], v252 offset:61440
	v_sub_f32_e32 v135, v135, v0
	v_exp_f32_e32 v135, v135
	v_add_f32_e32 v130, v134, v130
	s_waitcnt lgkmcnt(4)
	v_mfma_f32_32x32x16_bf16 v[18:33], v[182:185], v[186:189], v[18:33]
	ds_read_b64_tr_b16 v[186:187], v253 offset:57344
	ds_read_b64_tr_b16 v[188:189], v253 offset:61440
	v_sub_f32_e32 v136, v136, v0
	v_exp_f32_e32 v136, v136
	v_add_f32_e32 v130, v135, v130
	s_waitcnt lgkmcnt(4)
	v_mfma_f32_32x32x16_bf16 v[2:17], v[182:185], v[190:193], v[2:17]
	ds_read_b64_tr_b16 v[182:183], v254 offset:57344
	ds_read_b64_tr_b16 v[184:185], v254 offset:61440
	v_sub_f32_e32 v137, v137, v0
	v_exp_f32_e32 v137, v137
	v_add_f32_e32 v130, v136, v130
	s_waitcnt lgkmcnt(4)
	v_mfma_f32_32x32x16_bf16 v[114:129], v[178:181], v[248:251], v[114:129]
	ds_read_b64_tr_b16 v[190:191], v195 offset:57344
	ds_read_b64_tr_b16 v[192:193], v195 offset:61440
	v_sub_f32_e32 v138, v138, v0
	v_exp_f32_e32 v138, v138
	v_add_f32_e32 v130, v137, v130
	s_waitcnt lgkmcnt(4)
	v_mfma_f32_32x32x16_bf16 v[98:113], v[178:181], v[186:189], v[98:113]
	ds_read_b64_tr_b16 v[186:187], v252 offset:57600
	ds_read_b64_tr_b16 v[188:189], v252 offset:61696
	v_sub_f32_e32 v139, v139, v0
	v_exp_f32_e32 v139, v139
	v_add_f32_e32 v130, v138, v130
	s_cmp_le_u32 s47, s44
	s_cbranch_scc0 .Lmy_a_nov2
	s_mov_b32 m0, s55
	s_nop 0
	global_load_lds_dwordx4 v[204:205], off
.Lmy_a_nov2:
	s_waitcnt lgkmcnt(4)
	v_mfma_f32_32x32x16_bf16 v[82:97], v[178:181], v[182:185], v[82:97]
	ds_read_b64_tr_b16 v[182:183], v253 offset:57600
	ds_read_b64_tr_b16 v[184:185], v253 offset:61696
	v_sub_f32_e32 v140, v140, v0
	v_exp_f32_e32 v140, v140
	v_add_f32_e32 v130, v139, v130
	s_waitcnt lgkmcnt(4)
	v_mfma_f32_32x32x16_bf16 v[66:81], v[178:181], v[190:193], v[66:81]
	ds_read_b64_tr_b16 v[190:191], v254 offset:57600
	ds_read_b64_tr_b16 v[192:193], v254 offset:61696
	v_sub_f32_e32 v141, v141, v0
	v_exp_f32_e32 v141, v141
	v_add_f32_e32 v130, v140, v130
	s_waitcnt lgkmcnt(4)
	v_mfma_f32_32x32x16_bf16 v[50:65], v[178:181], v[186:189], v[50:65]
	ds_read_b64_tr_b16 v[186:187], v195 offset:57600
	ds_read_b64_tr_b16 v[188:189], v195 offset:61696
	v_sub_f32_e32 v142, v142, v0
	v_exp_f32_e32 v142, v142
	v_add_f32_e32 v130, v141, v130
	s_waitcnt lgkmcnt(4)
	v_mfma_f32_32x32x16_bf16 v[34:49], v[178:181], v[182:185], v[34:49]
	v_sub_f32_e32 v143, v143, v0
	v_exp_f32_e32 v143, v143
	v_add_f32_e32 v130, v142, v130
	s_waitcnt lgkmcnt(2)
	v_mfma_f32_32x32x16_bf16 v[18:33], v[178:181], v[190:193], v[18:33]
	v_sub_f32_e32 v144, v144, v0
	v_exp_f32_e32 v144, v144
	v_add_f32_e32 v130, v143, v130
	s_waitcnt lgkmcnt(0)
	v_mfma_f32_32x32x16_bf16 v[2:17], v[178:181], v[186:189], v[2:17]
	v_sub_f32_e32 v145, v145, v0
	v_exp_f32_e32 v145, v145
	v_add_f32_e32 v130, v144, v130
	s_cbranch_vccz .LBB0_295
	ds_write_b32 v226, v247
	ds_read_b128 v[190:193], v227 offset:96
	ds_read_b128 v[186:189], v227 offset:64
	ds_read_b128 v[182:185], v227 offset:32
	ds_read_b128 v[178:181], v227
	s_waitcnt lgkmcnt(3)
	v_pk_mul_f32 v[128:129], v[128:129], v[192:193]
	s_waitcnt lgkmcnt(2)
	v_pk_mul_f32 v[124:125], v[124:125], v[188:189]
	s_waitcnt lgkmcnt(1)
	v_pk_mul_f32 v[120:121], v[120:121], v[184:185]
	s_waitcnt lgkmcnt(0)
	v_pk_mul_f32 v[116:117], v[116:117], v[180:181]
	v_pk_mul_f32 v[126:127], v[126:127], v[190:191]
	v_pk_mul_f32 v[122:123], v[122:123], v[186:187]
	v_pk_mul_f32 v[118:119], v[118:119], v[182:183]
	v_pk_mul_f32 v[114:115], v[114:115], v[178:179]
	v_pk_mul_f32 v[112:113], v[112:113], v[192:193]
	v_pk_mul_f32 v[108:109], v[108:109], v[188:189]
	v_pk_mul_f32 v[104:105], v[104:105], v[184:185]
	v_pk_mul_f32 v[100:101], v[100:101], v[180:181]
	v_pk_mul_f32 v[110:111], v[110:111], v[190:191]
	v_pk_mul_f32 v[106:107], v[106:107], v[186:187]
	v_pk_mul_f32 v[102:103], v[102:103], v[182:183]
	v_pk_mul_f32 v[98:99], v[98:99], v[178:179]
	v_pk_mul_f32 v[96:97], v[96:97], v[192:193]
	v_pk_mul_f32 v[92:93], v[92:93], v[188:189]
	v_pk_mul_f32 v[88:89], v[88:89], v[184:185]
	v_pk_mul_f32 v[84:85], v[84:85], v[180:181]
	v_pk_mul_f32 v[94:95], v[94:95], v[190:191]
	v_pk_mul_f32 v[90:91], v[90:91], v[186:187]
	v_pk_mul_f32 v[86:87], v[86:87], v[182:183]
	v_pk_mul_f32 v[82:83], v[82:83], v[178:179]
	v_pk_mul_f32 v[80:81], v[80:81], v[192:193]
	v_pk_mul_f32 v[76:77], v[76:77], v[188:189]
	v_pk_mul_f32 v[72:73], v[72:73], v[184:185]
	v_pk_mul_f32 v[68:69], v[68:69], v[180:181]
	v_pk_mul_f32 v[78:79], v[78:79], v[190:191]
	v_pk_mul_f32 v[74:75], v[74:75], v[186:187]
	v_pk_mul_f32 v[70:71], v[70:71], v[182:183]
	v_pk_mul_f32 v[66:67], v[66:67], v[178:179]
	v_pk_mul_f32 v[64:65], v[64:65], v[192:193]
	v_pk_mul_f32 v[60:61], v[60:61], v[188:189]
	v_pk_mul_f32 v[56:57], v[56:57], v[184:185]
	v_pk_mul_f32 v[52:53], v[52:53], v[180:181]
	v_pk_mul_f32 v[62:63], v[62:63], v[190:191]
	v_pk_mul_f32 v[58:59], v[58:59], v[186:187]
	v_pk_mul_f32 v[54:55], v[54:55], v[182:183]
	v_pk_mul_f32 v[50:51], v[50:51], v[178:179]
	v_pk_mul_f32 v[48:49], v[48:49], v[192:193]
	v_pk_mul_f32 v[44:45], v[44:45], v[188:189]
	v_pk_mul_f32 v[40:41], v[40:41], v[184:185]
	v_pk_mul_f32 v[36:37], v[36:37], v[180:181]
	v_pk_mul_f32 v[46:47], v[46:47], v[190:191]
	v_pk_mul_f32 v[42:43], v[42:43], v[186:187]
	v_pk_mul_f32 v[38:39], v[38:39], v[182:183]
	v_pk_mul_f32 v[34:35], v[34:35], v[178:179]
	v_pk_mul_f32 v[32:33], v[32:33], v[192:193]
	v_pk_mul_f32 v[28:29], v[28:29], v[188:189]
	v_pk_mul_f32 v[24:25], v[24:25], v[184:185]
	v_pk_mul_f32 v[20:21], v[20:21], v[180:181]
	v_pk_mul_f32 v[30:31], v[30:31], v[190:191]
	v_pk_mul_f32 v[26:27], v[26:27], v[186:187]
	v_pk_mul_f32 v[22:23], v[22:23], v[182:183]
	v_pk_mul_f32 v[18:19], v[18:19], v[178:179]
	v_pk_mul_f32 v[16:17], v[16:17], v[192:193]
	v_pk_mul_f32 v[12:13], v[12:13], v[188:189]
	v_pk_mul_f32 v[8:9], v[8:9], v[184:185]
	v_pk_mul_f32 v[4:5], v[4:5], v[180:181]
	v_pk_mul_f32 v[14:15], v[14:15], v[190:191]
	v_pk_mul_f32 v[10:11], v[10:11], v[186:187]
	v_pk_mul_f32 v[6:7], v[6:7], v[182:183]
	v_pk_mul_f32 v[2:3], v[2:3], v[178:179]

.LBB0_1615:
	v_add_u32_e32 v0, s2, v199
	ds_read_b128 v[130:133], v0
	s_add_i32 s0, s45, -2
	ds_read_b128 v[188:191], v0 offset:1024
	s_waitcnt lgkmcnt(1)
	v_mfma_f32_32x32x16_bf16 v[130:145], v[130:133], v[146:149], 0
	ds_read_b128 v[248:251], v0 offset:2048
	s_waitcnt lgkmcnt(1)
	v_mfma_f32_32x32x16_bf16 v[130:145], v[188:191], v[150:153], v[130:145]
	ds_read_b128 v[188:191], v0 offset:3072
	s_cmp_lt_u32 s45, s42
	s_cbranch_scc0 .Lmy_b_nok1
	s_mov_b32 m0, s52
	s_nop 0
	global_load_lds_dwordx4 v[210:211], off
.Lmy_b_nok1:
	s_waitcnt lgkmcnt(1)
	v_mfma_f32_32x32x16_bf16 v[130:145], v[248:251], v[154:157], v[130:145]
	ds_read_b128 v[248:251], v0 offset:4096
	s_waitcnt lgkmcnt(1)
	v_mfma_f32_32x32x16_bf16 v[130:145], v[188:191], v[158:161], v[130:145]
	ds_read_b128 v[188:191], v0 offset:5120
	s_waitcnt lgkmcnt(1)
	v_mfma_f32_32x32x16_bf16 v[130:145], v[248:251], v[162:165], v[130:145]
	ds_read_b128 v[248:251], v0 offset:6144
	s_cmp_lt_u32 s45, s42
	s_cbranch_scc0 .Lmy_b_nok2
	s_mov_b32 m0, s53
	s_nop 0
	global_load_lds_dwordx4 v[208:209], off
.Lmy_b_nok2:
	s_waitcnt lgkmcnt(1)
	v_mfma_f32_32x32x16_bf16 v[130:145], v[188:191], v[166:169], v[130:145]
	ds_read_b128 v[188:191], v0 offset:7168
	s_waitcnt lgkmcnt(1)
	v_mfma_f32_32x32x16_bf16 v[130:145], v[248:251], v[170:173], v[130:145]
	s_waitcnt lgkmcnt(0)
	v_mfma_f32_32x32x16_bf16 v[130:145], v[188:191], v[174:177], v[130:145]
	s_cmp_lt_u32 s0, s41
	s_cbranch_scc1 .LBB0_1617
	v_add_u32_e32 v0, s44, v223
	v_add_u32_e32 v187, 32, v0
	v_cmp_lt_u32_e32 vcc, v187, v201
	s_nop 7
	v_cndmask_b32_e32 v131, v246, v131, vcc
	v_cmp_le_u32_e32 vcc, v187, v201
	v_add_u32_e32 v187, 34, v0
	s_nop 0
	v_cndmask_b32_e32 v130, v246, v130, vcc
	v_cmp_le_u32_e32 vcc, v187, v201
	v_add_u32_e32 v187, 35, v0
	s_nop 0
	v_cndmask_b32_e32 v132, v246, v132, vcc
	v_cmp_le_u32_e32 vcc, v187, v201
	v_add_u32_e32 v187, 40, v0
	s_nop 0
	v_cndmask_b32_e32 v133, v246, v133, vcc
	v_cmp_le_u32_e32 vcc, v187, v201
	v_add_u32_e32 v187, 41, v0
	s_nop 0
	v_cndmask_b32_e32 v134, v246, v134, vcc
	v_cmp_le_u32_e32 vcc, v187, v201
	v_add_u32_e32 v187, 42, v0
	s_nop 0
	v_cndmask_b32_e32 v135, v246, v135, vcc
	v_cmp_le_u32_e32 vcc, v187, v201
	v_add_u32_e32 v187, 43, v0
	s_nop 0
	v_cndmask_b32_e32 v136, v246, v136, vcc
	v_cmp_le_u32_e32 vcc, v187, v201
	v_add_u32_e32 v187, 48, v0
	s_nop 0
	v_cndmask_b32_e32 v137, v246, v137, vcc
	v_cmp_le_u32_e32 vcc, v187, v201
	v_add_u32_e32 v187, 49, v0
	s_nop 0
	v_cndmask_b32_e32 v138, v246, v138, vcc
	v_cmp_le_u32_e32 vcc, v187, v201
	v_add_u32_e32 v187, 50, v0
	s_nop 0
	v_cndmask_b32_e32 v139, v246, v139, vcc
	v_cmp_le_u32_e32 vcc, v187, v201
	v_add_u32_e32 v187, 51, v0
	s_nop 0
	v_cndmask_b32_e32 v140, v246, v140, vcc
	v_cmp_le_u32_e32 vcc, v187, v201
	v_add_u32_e32 v187, 56, v0
	s_nop 0
	v_cndmask_b32_e32 v141, v246, v141, vcc
	v_cmp_le_u32_e32 vcc, v187, v201
	v_add_u32_e32 v187, 57, v0
	s_nop 0
	v_cndmask_b32_e32 v142, v246, v142, vcc
	v_cmp_le_u32_e32 vcc, v187, v201
	v_add_u32_e32 v187, 58, v0
	v_add_u32_e32 v0, 59, v0
	v_cndmask_b32_e32 v143, v246, v143, vcc
	v_cmp_le_u32_e32 vcc, v187, v201
	s_nop 1
	v_cndmask_b32_e32 v144, v246, v144, vcc
	v_cmp_le_u32_e32 vcc, v0, v201
	s_nop 1
	v_cndmask_b32_e32 v145, v246, v145, vcc
.LBB0_1617:
	s_nop 9
	v_max3_f32 v0, v130, v131, v132
	v_max3_f32 v187, v133, v134, v135
	v_max3_f32 v188, v136, v137, v138
	v_max3_f32 v189, v139, v140, v141
	v_max3_f32 v0, v0, v142, v143
	v_max3_f32 v187, v187, v144, v145
	v_max3_f32 v0, v0, v187, v188
	v_max_f32_e32 v0, v0, v189
	v_mov_b32_e32 v187, v0
	s_nop 1
	v_permlane32_swap_b32_e32 v0, v187
	s_lshl_b32 s0, s47, 14
	v_max_f32_e32 v0, v0, v187
	v_add_f32_e32 v187, 0x41000000, v186
	s_add_i32 s3, s0, 0
	v_cmp_gt_f32_e32 vcc, v0, v187
	s_cmp_eq_u64 vcc, 0
	v_max_f32_e32 v0, v186, v0
	s_cselect_b64 s[0:1], -1, 0
	v_cndmask_b32_e64 v0, v0, v186, s[0:1]
	v_add_u32_e32 v252, s3, v224
	v_sub_f32_e32 v247, v186, v0
	v_add_u32_e32 v253, s3, v228
	ds_read_b64_tr_b16 v[186:187], v252 offset:49152
	ds_read_b64_tr_b16 v[188:189], v252 offset:53248
	ds_read_b64_tr_b16 v[190:191], v253 offset:49152
	ds_read_b64_tr_b16 v[192:193], v253 offset:53248
	v_exp_f32_e32 v247, v247
	v_add_u32_e32 v254, s3, v229
	ds_read_b64_tr_b16 v[248:249], v254 offset:49152
	ds_read_b64_tr_b16 v[250:251], v254 offset:53248
	s_waitcnt lgkmcnt(4)
	v_mfma_f32_32x32x16_bf16 v[114:129], v[182:185], v[186:189], v[114:129]
	v_add_u32_e32 v195, s3, v230
	ds_read_b64_tr_b16 v[186:187], v195 offset:49152
	ds_read_b64_tr_b16 v[188:189], v195 offset:53248
	v_sub_f32_e32 v130, v130, v0
	v_exp_f32_e32 v1, v130
	s_waitcnt lgkmcnt(4)
	v_mfma_f32_32x32x16_bf16 v[98:113], v[182:185], v[190:193], v[98:113]
	ds_read_b64_tr_b16 v[190:191], v252 offset:49408
	ds_read_b64_tr_b16 v[192:193], v252 offset:53504
	v_sub_f32_e32 v131, v131, v0
	v_exp_f32_e32 v131, v131
	v_add_f32_e32 v130, 0, v1
	s_waitcnt lgkmcnt(4)
	v_mfma_f32_32x32x16_bf16 v[82:97], v[182:185], v[248:251], v[82:97]
	ds_read_b64_tr_b16 v[248:249], v253 offset:49408
	ds_read_b64_tr_b16 v[250:251], v253 offset:53504
	v_sub_f32_e32 v132, v132, v0
	v_exp_f32_e32 v132, v132
	v_add_f32_e32 v130, v131, v130
	s_waitcnt lgkmcnt(4)
	v_mfma_f32_32x32x16_bf16 v[66:81], v[182:185], v[186:189], v[66:81]
	ds_read_b64_tr_b16 v[186:187], v254 offset:49408
	ds_read_b64_tr_b16 v[188:189], v254 offset:53504
	v_sub_f32_e32 v133, v133, v0
	v_exp_f32_e32 v133, v133
	v_add_f32_e32 v130, v132, v130
	s_cmp_le_u32 s45, s42
	s_cbranch_scc0 .Lmy_b_nov1
	s_mov_b32 m0, s54
	s_nop 0
	global_load_lds_dwordx4 v[206:207], off
.Lmy_b_nov1:
	s_waitcnt lgkmcnt(4)
	v_mfma_f32_32x32x16_bf16 v[50:65], v[182:185], v[190:193], v[50:65]
	ds_read_b64_tr_b16 v[190:191], v195 offset:49408
	ds_read_b64_tr_b16 v[192:193], v195 offset:53504
	v_sub_f32_e32 v134, v134, v0
	v_exp_f32_e32 v134, v134
	v_add_f32_e32 v130, v133, v130
	s_waitcnt lgkmcnt(4)
	v_mfma_f32_32x32x16_bf16 v[34:49], v[182:185], v[248:251], v[34:49]
	ds_read_b64_tr_b16 v[248:249], v252 offset:57344
	ds_read_b64_tr_b16 v[250:251], v252 offset:61440
	v_sub_f32_e32 v135, v135, v0
	v_exp_f32_e32 v135, v135
	v_add_f32_e32 v130, v134, v130
	s_waitcnt lgkmcnt(4)
	v_mfma_f32_32x32x16_bf16 v[18:33], v[182:185], v[186:189], v[18:33]
	ds_read_b64_tr_b16 v[186:187], v253 offset:57344
	ds_read_b64_tr_b16 v[188:189], v253 offset:61440
	v_sub_f32_e32 v136, v136, v0
	v_exp_f32_e32 v136, v136
	v_add_f32_e32 v130, v135, v130
	s_waitcnt lgkmcnt(4)
	v_mfma_f32_32x32x16_bf16 v[2:17], v[182:185], v[190:193], v[2:17]
	ds_read_b64_tr_b16 v[182:183], v254 offset:57344
	ds_read_b64_tr_b16 v[184:185], v254 offset:61440
	v_sub_f32_e32 v137, v137, v0
	v_exp_f32_e32 v137, v137
	v_add_f32_e32 v130, v136, v130
	s_waitcnt lgkmcnt(4)
	v_mfma_f32_32x32x16_bf16 v[114:129], v[178:181], v[248:251], v[114:129]
	ds_read_b64_tr_b16 v[190:191], v195 offset:57344
	ds_read_b64_tr_b16 v[192:193], v195 offset:61440
	v_sub_f32_e32 v138, v138, v0
	v_exp_f32_e32 v138, v138
	v_add_f32_e32 v130, v137, v130
	s_waitcnt lgkmcnt(4)
	v_mfma_f32_32x32x16_bf16 v[98:113], v[178:181], v[186:189], v[98:113]
	ds_read_b64_tr_b16 v[186:187], v252 offset:57600
	ds_read_b64_tr_b16 v[188:189], v252 offset:61696
	v_sub_f32_e32 v139, v139, v0
	v_exp_f32_e32 v139, v139
	v_add_f32_e32 v130, v138, v130
	s_cmp_le_u32 s45, s42
	s_cbranch_scc0 .Lmy_b_nov2
	s_mov_b32 m0, s55
	s_nop 0
	global_load_lds_dwordx4 v[204:205], off
